# LDS bank-conflict fix: the four column groups of the epilogue weight broadcast are skewed by 16 bytes across the wave's two ring pieces
# speedup vs baseline: 1.0086x; 1.0006x over previous
; #define LAS __attribute__((address_space(3)))
;     __device__ __forceinline__ void operator()(f32x4 (&acc)[2][2][4][2], const Unit& u, int wr, int wc, int fr, int fq, const LAS float* rtab) const {
;         const int c0 = u.pn * 128 + wc * 32 + 8 * fq;
; #pragma unroll
;         for (int ai = 0; ai < 2; ++ai)
; #pragma unroll
;             for (int m = 0; m < 4; ++m) { const float r = rtab[ai * HALF + wr * 64 + m * 16 + fr];
; #pragma unroll
;                 for (int bj = 0; bj < 2; ++bj)
; #pragma unroll
;                     for (int n = 0; n < 2; ++n) acc[ai][bj][m][n] = acc[ai][bj][m][n] * r; }
;     ...
;             const f32x4 wg0 = *(const f32x4*)(cw + cn), wg1 = *(const f32x4*)(cw + UP_N + cn), wg2 = *(const f32x4*)(cw + 2 * UP_N + cn), bg = *(const f32x4*)(cb + cn);
;             const f32x4 wu0 = *(const f32x4*)(cw + DFF + cn), wu1 = *(const f32x4*)(cw + UP_N + DFF + cn), wu2 = *(const f32x4*)(cw + 2 * UP_N + DFF + cn), bu = *(const f32x4*)(cb + DFF + cn);
.LBB0_839:
	v_lshl_add_u32 v252, s1, 10, v192
	v_mad_u32_u24 v252, v134, 12, v252
	ds_read_b128 v[228:231], v252
	ds_read_b128 v[232:235], v252 offset:512
	v_lshl_or_b32 v213, s0, 7, v193
	v_lshlrev_b32_e32 v253, 2, v213
	v_and_b32_e32 v217, 63, v208
	v_lshrrev_b32_e32 v142, 1, v134
	v_and_b32_e32 v143, 1, v134
	v_and_b32_e32 v178, 3, v142
	v_cmp_eq_u32_e64 s[56:57], 3, v178
	v_cmp_lt_u32_e64 s[54:55], 3, v142
	v_mul_u32_u24_e32 v210, 0xb000, v178
	v_mov_b32_e32 v211, 0
	v_cndmask_b32_e64 v210, v210, 0, s[56:57]
	v_lshl_add_u32 v210, v143, 4, v210
	v_lshl_add_u32 v210, v213, 2, v210
	v_add_u32_e32 v179, 0x5800, v210
	v_cndmask_b32_e64 v210, v210, v179, s[54:55]
	v_mov_b32_e32 v218, s34
	v_mov_b32_e32 v219, s35
	v_mov_b32_e32 v252, s36
	v_mov_b32_e32 v253, s37
	v_cndmask_b32_e64 v218, v218, v252, s[56:57]
	v_cndmask_b32_e64 v219, v219, v253, s[56:57]
	v_lshl_add_u64 v[210:211], v[218:219], 0, v[210:211]
	global_load_dwordx4 v[224:227], v[210:211], off
	v_bfe_u32 v212, v217, 4, 2
	v_and_b32_e32 v195, 1, v212
	v_lshlrev_b32_e32 v195, 8, v195
	v_lshrrev_b32_e32 v179, 1, v212
	v_lshl_add_u32 v195, v179, 13, v195
	v_lshl_add_u32 v195, v212, 4, v195
	v_add_u32_e32 v212, s19, v195
	v_lshl_add_u32 v195, v134, 4, v212
	s_waitcnt lgkmcnt(0)
	v_pk_mul_f32 v[124:125], v[124:125], v[228:229] op_sel_hi:[1,0]
	v_pk_mul_f32 v[126:127], v[126:127], v[228:229] op_sel_hi:[1,0]
	v_pk_mul_f32 v[120:121], v[120:121], v[228:229] op_sel_hi:[1,0]
	v_pk_mul_f32 v[122:123], v[122:123], v[228:229] op_sel_hi:[1,0]
	v_pk_mul_f32 v[116:117], v[116:117], v[228:229] op_sel_hi:[1,0]
	v_pk_mul_f32 v[118:119], v[118:119], v[228:229] op_sel_hi:[1,0]
	v_pk_mul_f32 v[112:113], v[112:113], v[228:229] op_sel_hi:[1,0]
	v_pk_mul_f32 v[114:115], v[114:115], v[228:229] op_sel_hi:[1,0]
	v_pk_mul_f32 v[68:69], v[68:69], v[228:229] op_sel:[0,1] op_sel_hi:[1,1]
	v_pk_mul_f32 v[70:71], v[70:71], v[228:229] op_sel:[0,1] op_sel_hi:[1,1]
	v_pk_mul_f32 v[64:65], v[64:65], v[228:229] op_sel:[0,1] op_sel_hi:[1,1]
	v_pk_mul_f32 v[66:67], v[66:67], v[228:229] op_sel:[0,1] op_sel_hi:[1,1]
	v_pk_mul_f32 v[52:53], v[52:53], v[228:229] op_sel:[0,1] op_sel_hi:[1,1]
	v_pk_mul_f32 v[54:55], v[54:55], v[228:229] op_sel:[0,1] op_sel_hi:[1,1]
	v_pk_mul_f32 v[48:49], v[48:49], v[228:229] op_sel:[0,1] op_sel_hi:[1,1]
	v_pk_mul_f32 v[50:51], v[50:51], v[228:229] op_sel:[0,1] op_sel_hi:[1,1]
	v_pk_mul_f32 v[60:61], v[60:61], v[230:231] op_sel_hi:[1,0]
	v_pk_mul_f32 v[62:63], v[62:63], v[230:231] op_sel_hi:[1,0]
	v_pk_mul_f32 v[20:21], v[20:21], v[230:231] op_sel_hi:[1,0]
	v_pk_mul_f32 v[22:23], v[22:23], v[230:231] op_sel_hi:[1,0]
	v_pk_mul_f32 v[44:45], v[44:45], v[230:231] op_sel_hi:[1,0]
	v_pk_mul_f32 v[46:47], v[46:47], v[230:231] op_sel_hi:[1,0]
	v_pk_mul_f32 v[16:17], v[16:17], v[230:231] op_sel_hi:[1,0]
	v_pk_mul_f32 v[18:19], v[18:19], v[230:231] op_sel_hi:[1,0]
	v_pk_mul_f32 v[108:109], v[108:109], v[230:231] op_sel:[0,1] op_sel_hi:[1,1]
	v_pk_mul_f32 v[110:111], v[110:111], v[230:231] op_sel:[0,1] op_sel_hi:[1,1]
	v_pk_mul_f32 v[104:105], v[104:105], v[230:231] op_sel:[0,1] op_sel_hi:[1,1]
	v_pk_mul_f32 v[106:107], v[106:107], v[230:231] op_sel:[0,1] op_sel_hi:[1,1]
	v_pk_mul_f32 v[100:101], v[100:101], v[230:231] op_sel:[0,1] op_sel_hi:[1,1]
	v_pk_mul_f32 v[102:103], v[102:103], v[230:231] op_sel:[0,1] op_sel_hi:[1,1]
	v_pk_mul_f32 v[96:97], v[96:97], v[230:231] op_sel:[0,1] op_sel_hi:[1,1]
	v_pk_mul_f32 v[98:99], v[98:99], v[230:231] op_sel:[0,1] op_sel_hi:[1,1]
	v_pk_mul_f32 v[92:93], v[92:93], v[232:233] op_sel_hi:[1,0]
	v_pk_mul_f32 v[94:95], v[94:95], v[232:233] op_sel_hi:[1,0]
	v_pk_mul_f32 v[88:89], v[88:89], v[232:233] op_sel_hi:[1,0]
	v_pk_mul_f32 v[90:91], v[90:91], v[232:233] op_sel_hi:[1,0]
	v_pk_mul_f32 v[84:85], v[84:85], v[232:233] op_sel_hi:[1,0]
	v_pk_mul_f32 v[86:87], v[86:87], v[232:233] op_sel_hi:[1,0]
	v_pk_mul_f32 v[80:81], v[80:81], v[232:233] op_sel_hi:[1,0]
	v_pk_mul_f32 v[82:83], v[82:83], v[232:233] op_sel_hi:[1,0]
	v_pk_mul_f32 v[36:37], v[36:37], v[232:233] op_sel:[0,1] op_sel_hi:[1,1]
	v_pk_mul_f32 v[38:39], v[38:39], v[232:233] op_sel:[0,1] op_sel_hi:[1,1]
	v_pk_mul_f32 v[12:13], v[12:13], v[232:233] op_sel:[0,1] op_sel_hi:[1,1]
	v_pk_mul_f32 v[14:15], v[14:15], v[232:233] op_sel:[0,1] op_sel_hi:[1,1]
	v_pk_mul_f32 v[28:29], v[28:29], v[232:233] op_sel:[0,1] op_sel_hi:[1,1]
	v_pk_mul_f32 v[30:31], v[30:31], v[232:233] op_sel:[0,1] op_sel_hi:[1,1]
	v_pk_mul_f32 v[8:9], v[8:9], v[232:233] op_sel:[0,1] op_sel_hi:[1,1]
	v_pk_mul_f32 v[10:11], v[10:11], v[232:233] op_sel:[0,1] op_sel_hi:[1,1]
	v_pk_mul_f32 v[32:33], v[32:33], v[234:235] op_sel_hi:[1,0]
	v_pk_mul_f32 v[34:35], v[34:35], v[234:235] op_sel_hi:[1,0]
	v_pk_mul_f32 v[4:5], v[4:5], v[234:235] op_sel_hi:[1,0]
	v_pk_mul_f32 v[6:7], v[6:7], v[234:235] op_sel_hi:[1,0]
	v_pk_mul_f32 v[24:25], v[24:25], v[234:235] op_sel_hi:[1,0]
	v_pk_mul_f32 v[26:27], v[26:27], v[234:235] op_sel_hi:[1,0]
	v_pk_mul_f32 v[0:1], v[0:1], v[234:235] op_sel_hi:[1,0]
	v_pk_mul_f32 v[2:3], v[2:3], v[234:235] op_sel_hi:[1,0]
	v_pk_mul_f32 v[76:77], v[76:77], v[234:235] op_sel:[0,1] op_sel_hi:[1,1]
	v_pk_mul_f32 v[78:79], v[78:79], v[234:235] op_sel:[0,1] op_sel_hi:[1,1]
	v_pk_mul_f32 v[56:57], v[56:57], v[234:235] op_sel:[0,1] op_sel_hi:[1,1]
	v_pk_mul_f32 v[58:59], v[58:59], v[234:235] op_sel:[0,1] op_sel_hi:[1,1]
	v_pk_mul_f32 v[72:73], v[72:73], v[234:235] op_sel:[0,1] op_sel_hi:[1,1]
	v_pk_mul_f32 v[74:75], v[74:75], v[234:235] op_sel:[0,1] op_sel_hi:[1,1]
	v_pk_mul_f32 v[40:41], v[40:41], v[234:235] op_sel:[0,1] op_sel_hi:[1,1]
	v_pk_mul_f32 v[42:43], v[42:43], v[234:235] op_sel:[0,1] op_sel_hi:[1,1]
	v_lshlrev_b32_e32 v235, 1, v213
; __device__ __forceinline__ unsigned cvt_pk_bf16(float lo, float hi) { unsigned r; asm volatile("v_cvt_pk_bf16_f32 %0, %1, %2" : "=v"(r) : "v"(lo), "v"(hi)); return r; }
;     __device__ __forceinline__ void operator()(f32x4 (&acc)[2][2][4][2], const Unit& u, int wr, int wc, int fr, int fq, const LAS float* rtab) const {
;     ...
;         for (int ai = 0; ai < 2; ++ai) {
;             const int blk = (u.pm * BM + ai * HALF + wr * 64) >> 6;
;             if (fr < 2) { bf16_t* rp = raw + ((size_t)blk * 4 + fr) * UP_N + c0;
;                 const f32x4 g0 = acc[ai][0][0][0], g1 = acc[ai][0][0][1], u0 = acc[ai][1][0][0], u1 = acc[ai][1][0][1];
;                 u32x4 w; w.x = cvt_pk_bf16(g0[0], g0[1]); w.y = cvt_pk_bf16(g0[2], g0[3]); w.z = cvt_pk_bf16(g1[0], g1[1]); w.w = cvt_pk_bf16(g1[2], g1[3]); *(u32x4*)rp = w;
;                 w.x = cvt_pk_bf16(u0[0], u0[1]); w.y = cvt_pk_bf16(u0[2], u0[3]); w.z = cvt_pk_bf16(u1[0], u1[1]); w.w = cvt_pk_bf16(u1[2], u1[3]); *(u32x4*)(rp + DFF) = w; }
;             if (fr >= 14) { bf16_t* rp = raw + ((size_t)blk * 4 + (fr - 12)) * UP_N + c0;
;                 const f32x4 g0 = acc[ai][0][3][0], g1 = acc[ai][0][3][1], u0 = acc[ai][1][3][0], u1 = acc[ai][1][3][1];
;                 u32x4 w; w.x = cvt_pk_bf16(g0[0], g0[1]); w.y = cvt_pk_bf16(g0[2], g0[3]); w.z = cvt_pk_bf16(g1[0], g1[1]); w.w = cvt_pk_bf16(g1[2], g1[3]); *(u32x4*)rp = w;
;                 w.x = cvt_pk_bf16(u0[0], u0[1]); w.y = cvt_pk_bf16(u0[2], u0[3]); w.z = cvt_pk_bf16(u1[0], u1[1]); w.w = cvt_pk_bf16(u1[2], u1[3]); *(u32x4*)(rp + DFF) = w; }
;         }
;     ...
;             const f32x4 wg0 = *(const f32x4*)(cw + cn), wg1 = *(const f32x4*)(cw + UP_N + cn), wg2 = *(const f32x4*)(cw + 2 * UP_N + cn), bg = *(const f32x4*)(cb + cn);
;             const f32x4 wu0 = *(const f32x4*)(cw + DFF + cn), wu1 = *(const f32x4*)(cw + UP_N + DFF + cn), wu2 = *(const f32x4*)(cw + 2 * UP_N + DFF + cn), bu = *(const f32x4*)(cb + DFF + cn);
	s_lshl_b32 s0, s18, 8
	s_add_i32 s0, s0, s69
	v_lshl_add_u32 v234, v134, 2, s0
	v_mul_lo_u32 v234, v234, s89
	v_add_u32_e32 v234, v234, v235
	v_cmp_eq_u32_e64 s[54:55], 0, v134
	v_cmp_eq_u32_e64 s[56:57], 15, v134
	s_lshl_b32 s0, s18, 4
	s_lshr_b32 s1, s69, 4
	s_add_i32 s0, s0, s1
	s_add_i32 s1, s0, 0
	s_mul_i32 s1, s1, s88
	s_add_u32 s58, s30, s1
	s_addc_u32 s59, s31, 0
	s_mov_b64 exec, s[54:55]
	v_cvt_pk_bf16_f32 v244, v124, v125
	v_cvt_pk_bf16_f32 v245, v126, v127
	v_cvt_pk_bf16_f32 v246, v120, v121
	v_cvt_pk_bf16_f32 v247, v122, v123
	v_cvt_pk_bf16_f32 v248, v116, v117
	v_cvt_pk_bf16_f32 v249, v118, v119
	v_cvt_pk_bf16_f32 v250, v112, v113
	v_cvt_pk_bf16_f32 v251, v114, v115
	global_store_dwordx4 v235, v[244:247], s[58:59]
	s_add_u32 s58, s58, 0x2c00
	s_addc_u32 s59, s59, 0
	global_store_dwordx4 v235, v[248:251], s[58:59]
	s_add_i32 s1, s0, 1
	s_mul_i32 s1, s1, s88
	s_add_u32 s58, s30, s1
	s_addc_u32 s59, s31, 0
	s_mov_b64 exec, s[54:55]
	v_cvt_pk_bf16_f32 v236, v68, v69
	v_cvt_pk_bf16_f32 v237, v70, v71
	v_cvt_pk_bf16_f32 v238, v64, v65
	v_cvt_pk_bf16_f32 v239, v66, v67
	v_cvt_pk_bf16_f32 v240, v52, v53
	v_cvt_pk_bf16_f32 v241, v54, v55
	v_cvt_pk_bf16_f32 v242, v48, v49
	v_cvt_pk_bf16_f32 v243, v50, v51
	global_store_dwordx4 v235, v[236:239], s[58:59]
	s_add_u32 s58, s58, 0x2c00
	s_addc_u32 s59, s59, 0
	global_store_dwordx4 v235, v[240:243], s[58:59]
	s_add_i32 s1, s0, 2
	s_mul_i32 s1, s1, s88
	s_add_u32 s58, s30, s1
	s_addc_u32 s59, s31, 0
	s_mov_b64 exec, s[56:57]
	v_cvt_pk_bf16_f32 v244, v60, v61
	v_cvt_pk_bf16_f32 v245, v62, v63
	v_cvt_pk_bf16_f32 v246, v20, v21
	v_cvt_pk_bf16_f32 v247, v22, v23
	v_cvt_pk_bf16_f32 v248, v44, v45
	v_cvt_pk_bf16_f32 v249, v46, v47
	v_cvt_pk_bf16_f32 v250, v16, v17
	v_cvt_pk_bf16_f32 v251, v18, v19
	global_store_dwordx4 v235, v[244:247], s[58:59]
	s_add_u32 s58, s58, 0x2c00
	s_addc_u32 s59, s59, 0
	global_store_dwordx4 v235, v[248:251], s[58:59]
	s_add_i32 s1, s0, 3
	s_mul_i32 s1, s1, s88
	s_add_u32 s58, s30, s1
	s_addc_u32 s59, s31, 0
	s_mov_b64 exec, s[56:57]
	v_cvt_pk_bf16_f32 v236, v108, v109
	v_cvt_pk_bf16_f32 v237, v110, v111
	v_cvt_pk_bf16_f32 v238, v104, v105
	v_cvt_pk_bf16_f32 v239, v106, v107
	v_cvt_pk_bf16_f32 v240, v100, v101
	v_cvt_pk_bf16_f32 v241, v102, v103
	v_cvt_pk_bf16_f32 v242, v96, v97
	v_cvt_pk_bf16_f32 v243, v98, v99
	global_store_dwordx4 v235, v[236:239], s[58:59]
	s_add_u32 s58, s58, 0x2c00
	s_addc_u32 s59, s59, 0
	global_store_dwordx4 v235, v[240:243], s[58:59]
	s_add_i32 s1, s0, 8
	s_mul_i32 s1, s1, s88
	s_add_u32 s58, s30, s1
	s_addc_u32 s59, s31, 0
	s_mov_b64 exec, s[54:55]
	v_cvt_pk_bf16_f32 v244, v92, v93
	v_cvt_pk_bf16_f32 v245, v94, v95
	v_cvt_pk_bf16_f32 v246, v88, v89
	v_cvt_pk_bf16_f32 v247, v90, v91
	v_cvt_pk_bf16_f32 v248, v84, v85
	v_cvt_pk_bf16_f32 v249, v86, v87
	v_cvt_pk_bf16_f32 v250, v80, v81
	v_cvt_pk_bf16_f32 v251, v82, v83
	global_store_dwordx4 v235, v[244:247], s[58:59]
	s_add_u32 s58, s58, 0x2c00
	s_addc_u32 s59, s59, 0
	global_store_dwordx4 v235, v[248:251], s[58:59]
	s_add_i32 s1, s0, 9
	s_mul_i32 s1, s1, s88
	s_add_u32 s58, s30, s1
	s_addc_u32 s59, s31, 0
	s_mov_b64 exec, s[54:55]
	v_cvt_pk_bf16_f32 v236, v36, v37
	v_cvt_pk_bf16_f32 v237, v38, v39
	v_cvt_pk_bf16_f32 v238, v12, v13
	v_cvt_pk_bf16_f32 v239, v14, v15
	v_cvt_pk_bf16_f32 v240, v28, v29
	v_cvt_pk_bf16_f32 v241, v30, v31
	v_cvt_pk_bf16_f32 v242, v8, v9
	v_cvt_pk_bf16_f32 v243, v10, v11
	global_store_dwordx4 v235, v[236:239], s[58:59]
	s_add_u32 s58, s58, 0x2c00
	s_addc_u32 s59, s59, 0
	global_store_dwordx4 v235, v[240:243], s[58:59]
	s_add_i32 s1, s0, 10
	s_mul_i32 s1, s1, s88
	s_add_u32 s58, s30, s1
	s_addc_u32 s59, s31, 0
	s_mov_b64 exec, s[56:57]
	v_cvt_pk_bf16_f32 v244, v32, v33
	v_cvt_pk_bf16_f32 v245, v34, v35
	v_cvt_pk_bf16_f32 v246, v4, v5
	v_cvt_pk_bf16_f32 v247, v6, v7
	v_cvt_pk_bf16_f32 v248, v24, v25
	v_cvt_pk_bf16_f32 v249, v26, v27
	v_cvt_pk_bf16_f32 v250, v0, v1
	v_cvt_pk_bf16_f32 v251, v2, v3
	global_store_dwordx4 v235, v[244:247], s[58:59]
	s_add_u32 s58, s58, 0x2c00
	s_addc_u32 s59, s59, 0
	global_store_dwordx4 v235, v[248:251], s[58:59]
	s_add_i32 s1, s0, 11
	s_mul_i32 s1, s1, s88
	s_add_u32 s58, s30, s1
	s_addc_u32 s59, s31, 0
	s_mov_b64 exec, s[56:57]
	v_cvt_pk_bf16_f32 v236, v76, v77
	v_cvt_pk_bf16_f32 v237, v78, v79
	v_cvt_pk_bf16_f32 v238, v56, v57
	v_cvt_pk_bf16_f32 v239, v58, v59
	v_cvt_pk_bf16_f32 v240, v72, v73
	v_cvt_pk_bf16_f32 v241, v74, v75
	v_cvt_pk_bf16_f32 v242, v40, v41
	v_cvt_pk_bf16_f32 v243, v42, v43
	global_store_dwordx4 v235, v[236:239], s[58:59]
	s_add_u32 s58, s58, 0x2c00
	s_addc_u32 s59, s59, 0
	global_store_dwordx4 v235, v[240:243], s[58:59]
	s_mov_b64 exec, -1
	s_waitcnt vmcnt(16)
	ds_write_b128 v195, v[224:227] offset:49152
	s_waitcnt lgkmcnt(0)
	ds_read_b128 v[144:147], v212 offset:49152
	ds_read_b128 v[152:155], v212 offset:49184
	ds_read_b128 v[160:163], v212 offset:49216
	ds_read_b128 v[168:171], v212 offset:49248
	ds_read_b128 v[180:183], v212 offset:49280
	ds_read_b128 v[188:191], v212 offset:49312
	ds_read_b128 v[200:203], v212 offset:49344
	ds_read_b128 v[220:223], v212 offset:49376
	ds_read_b128 v[148:151], v212 offset:49168
	ds_read_b128 v[156:159], v212 offset:49200
	ds_read_b128 v[164:167], v212 offset:49232
	ds_read_b128 v[172:175], v212 offset:49264
	ds_read_b128 v[184:187], v212 offset:49296
	ds_read_b128 v[196:199], v212 offset:49328
	ds_read_b128 v[204:207], v212 offset:49360
	ds_read_b128 v[224:227], v212 offset:49392
	s_waitcnt lgkmcnt(12)
; __device__ __forceinline__ unsigned cvt_pk_bf16(float lo, float hi) { unsigned r; asm volatile("v_cvt_pk_bf16_f32 %0, %1, %2" : "=v"(r) : "v"(lo), "v"(hi)); return r; }
; template <int CTRL> __device__ __forceinline__ float dppz(float v) { return __int_as_float(__builtin_amdgcn_update_dpp(0, __float_as_int(v), CTRL, 0xf, 0xf, true)); }
;     __device__ __forceinline__ void operator()(f32x4 (&acc)[2][2][4][2], const Unit& u, int wr, int wc, int fr, int fq, const LAS float* rtab) const {
;     ...
;                     for (int jj = 0; jj < 4; ++jj) {
;                         const float gc = acc[ai][0][m][n][jj], uc = acc[ai][1][m][n][jj];
;                         const float gb = m > 0 ? acc[ai][0][m - 1][n][jj] : 0.f, ga = m < 3 ? acc[ai][0][m + 1][n][jj] : 0.f;
;                         const float ub = m > 0 ? acc[ai][1][m - 1][n][jj] : 0.f, ua = m < 3 ? acc[ai][1][m + 1][n][jj] : 0.f;
;                         const float gp = dppz<0x111>(gc) + dppz<0x10F>(gb), gn = dppz<0x101>(gc) + dppz<0x11F>(ga);
;                         const float up = dppz<0x111>(uc) + dppz<0x10F>(ub), un = dppz<0x101>(uc) + dppz<0x11F>(ua);
;                         const float hg = wg0[jj] * gp + wg1[jj] * gc + wg2[jj] * gn + bg[jj];
;                         const float hu = wu0[jj] * up + wu1[jj] * uc + wu2[jj] * un + bu[jj];
;                         const float sg = __builtin_amdgcn_rcpf(1.f + __builtin_amdgcn_exp2f(-1.4426950408889634f * hg));
;                         y[jj] = hg * sg * hu; }
;                     u32x2 pk; pk.x = cvt_pk_bf16(y[0], y[1]); pk.y = cvt_pk_bf16(y[2], y[3]);
;                     if (n == 0) ypk[ai][m] = pk;
;                     else {
;                         const bool deferred = (m == 0 && fr == 0) || (m == 3 && fr == 15);
;                         if (!deferred) { u32x4 w; w.x = ypk[ai][m].x; w.y = ypk[ai][m].y; w.z = pk.x; w.w = pk.y; *(u32x4*)(act + (size_t)(r64 + m * 16 + fr) * DFF + c0) = w; } }
	s_mov_b32 s54, 0xbfb8aa3b
	s_mov_b32 s56, 1.0
	v_pk_fma_f32 v[142:143], v[152:153], v[124:125], v[168:169]
	v_pk_fma_f32 v[178:179], v[152:153], v[68:69], v[168:169]
	v_pk_fma_f32 v[210:211], v[152:153], v[60:61], v[168:169]
	v_pk_fma_f32 v[212:213], v[152:153], v[108:109], v[168:169]
	v_pk_fma_f32 v[142:143], v[160:161], v[68:69], v[142:143]
	v_pk_fma_f32 v[178:179], v[144:145], v[124:125], v[178:179]
	v_pk_fma_f32 v[210:211], v[144:145], v[68:69], v[210:211]
	v_pk_fma_f32 v[212:213], v[144:145], v[60:61], v[212:213]
	v_pk_fma_f32 v[178:179], v[160:161], v[60:61], v[178:179]
	v_pk_fma_f32 v[210:211], v[160:161], v[108:109], v[210:211]
	v_fmac_f32_dpp v142, v108, v144 row_shr:1 row_mask:0xf bank_mask:0xf bound_ctrl:1
	v_fmac_f32_dpp v212, v124, v160 row_shl:1 row_mask:0xf bank_mask:0xf bound_ctrl:1
	v_fmac_f32_dpp v143, v109, v145 row_shr:1 row_mask:0xf bank_mask:0xf bound_ctrl:1
	v_fmac_f32_dpp v213, v125, v161 row_shl:1 row_mask:0xf bank_mask:0xf bound_ctrl:1
	v_pk_mul_f32 v[218:219], v[142:143], s[54:55] op_sel_hi:[1,0]
	v_pk_mul_f32 v[252:253], v[178:179], s[54:55] op_sel_hi:[1,0]
	v_pk_mul_f32 v[228:229], v[210:211], s[54:55] op_sel_hi:[1,0]
	v_pk_mul_f32 v[230:231], v[212:213], s[54:55] op_sel_hi:[1,0]
	v_exp_f32_e32 v218, v218
	v_exp_f32_e32 v219, v219
	v_exp_f32_e32 v252, v252
	v_exp_f32_e32 v253, v253
	v_exp_f32_e32 v228, v228
	v_exp_f32_e32 v229, v229
	v_exp_f32_e32 v230, v230
	v_exp_f32_e32 v231, v231
	v_pk_add_f32 v[218:219], v[218:219], s[56:57] op_sel_hi:[1,0]
	v_pk_add_f32 v[252:253], v[252:253], s[56:57] op_sel_hi:[1,0]
	v_pk_add_f32 v[228:229], v[228:229], s[56:57] op_sel_hi:[1,0]
	v_pk_add_f32 v[230:231], v[230:231], s[56:57] op_sel_hi:[1,0]
	v_rcp_f32_e32 v218, v218
	v_rcp_f32_e32 v219, v219
	v_rcp_f32_e32 v252, v252
	v_rcp_f32_e32 v253, v253
	v_rcp_f32_e32 v228, v228
	v_rcp_f32_e32 v229, v229
	v_rcp_f32_e32 v230, v230
	v_rcp_f32_e32 v231, v231
	v_pk_mul_f32 v[142:143], v[142:143], v[218:219]
	v_pk_mul_f32 v[178:179], v[178:179], v[252:253]
	v_pk_mul_f32 v[210:211], v[210:211], v[228:229]
	v_pk_mul_f32 v[212:213], v[212:213], v[230:231]
	s_waitcnt lgkmcnt(8)
	v_pk_fma_f32 v[218:219], v[188:189], v[116:117], v[220:221]
	v_pk_fma_f32 v[252:253], v[188:189], v[52:53], v[220:221]
	v_pk_fma_f32 v[228:229], v[188:189], v[44:45], v[220:221]
	v_pk_fma_f32 v[230:231], v[188:189], v[100:101], v[220:221]
	v_pk_fma_f32 v[218:219], v[200:201], v[52:53], v[218:219]
	v_pk_fma_f32 v[252:253], v[180:181], v[116:117], v[252:253]
	v_pk_fma_f32 v[228:229], v[180:181], v[52:53], v[228:229]
	v_pk_fma_f32 v[230:231], v[180:181], v[44:45], v[230:231]
	v_pk_fma_f32 v[252:253], v[200:201], v[44:45], v[252:253]
	v_pk_fma_f32 v[228:229], v[200:201], v[100:101], v[228:229]
	v_fmac_f32_dpp v218, v100, v180 row_shr:1 row_mask:0xf bank_mask:0xf bound_ctrl:1
	v_fmac_f32_dpp v230, v116, v200 row_shl:1 row_mask:0xf bank_mask:0xf bound_ctrl:1
	v_fmac_f32_dpp v219, v101, v181 row_shr:1 row_mask:0xf bank_mask:0xf bound_ctrl:1
	v_fmac_f32_dpp v231, v117, v201 row_shl:1 row_mask:0xf bank_mask:0xf bound_ctrl:1
	v_pk_mul_f32 v[142:143], v[142:143], v[218:219]
	v_pk_mul_f32 v[178:179], v[178:179], v[252:253]
	v_pk_mul_f32 v[210:211], v[210:211], v[228:229]
	v_pk_mul_f32 v[212:213], v[212:213], v[230:231]
	v_cvt_pk_bf16_f32 v236, v142, v143
	v_cvt_pk_bf16_f32 v240, v178, v179
	v_cvt_pk_bf16_f32 v244, v210, v211
	v_cvt_pk_bf16_f32 v248, v212, v213
	v_pk_fma_f32 v[142:143], v[154:155], v[126:127], v[170:171]
	v_pk_fma_f32 v[178:179], v[154:155], v[70:71], v[170:171]
	v_pk_fma_f32 v[210:211], v[154:155], v[62:63], v[170:171]
	v_pk_fma_f32 v[212:213], v[154:155], v[110:111], v[170:171]
	v_pk_fma_f32 v[142:143], v[162:163], v[70:71], v[142:143]
	v_pk_fma_f32 v[178:179], v[146:147], v[126:127], v[178:179]
	v_pk_fma_f32 v[210:211], v[146:147], v[70:71], v[210:211]
	v_pk_fma_f32 v[212:213], v[146:147], v[62:63], v[212:213]
	v_pk_fma_f32 v[178:179], v[162:163], v[62:63], v[178:179]
	v_pk_fma_f32 v[210:211], v[162:163], v[110:111], v[210:211]
	v_fmac_f32_dpp v142, v110, v146 row_shr:1 row_mask:0xf bank_mask:0xf bound_ctrl:1
	v_fmac_f32_dpp v212, v126, v162 row_shl:1 row_mask:0xf bank_mask:0xf bound_ctrl:1
	v_fmac_f32_dpp v143, v111, v147 row_shr:1 row_mask:0xf bank_mask:0xf bound_ctrl:1
	v_fmac_f32_dpp v213, v127, v163 row_shl:1 row_mask:0xf bank_mask:0xf bound_ctrl:1
	v_pk_mul_f32 v[218:219], v[142:143], s[54:55] op_sel_hi:[1,0]
	v_pk_mul_f32 v[252:253], v[178:179], s[54:55] op_sel_hi:[1,0]
	v_pk_mul_f32 v[228:229], v[210:211], s[54:55] op_sel_hi:[1,0]
	v_pk_mul_f32 v[230:231], v[212:213], s[54:55] op_sel_hi:[1,0]
	v_exp_f32_e32 v218, v218
	v_exp_f32_e32 v219, v219
	v_exp_f32_e32 v252, v252
	v_exp_f32_e32 v253, v253
	v_exp_f32_e32 v228, v228
	v_exp_f32_e32 v229, v229
	v_exp_f32_e32 v230, v230
	v_exp_f32_e32 v231, v231
	v_pk_add_f32 v[218:219], v[218:219], s[56:57] op_sel_hi:[1,0]
	v_pk_add_f32 v[252:253], v[252:253], s[56:57] op_sel_hi:[1,0]
	v_pk_add_f32 v[228:229], v[228:229], s[56:57] op_sel_hi:[1,0]
	v_pk_add_f32 v[230:231], v[230:231], s[56:57] op_sel_hi:[1,0]
	v_rcp_f32_e32 v218, v218
	v_rcp_f32_e32 v219, v219
	v_rcp_f32_e32 v252, v252
	v_rcp_f32_e32 v253, v253
	v_rcp_f32_e32 v228, v228
	v_rcp_f32_e32 v229, v229
	v_rcp_f32_e32 v230, v230
	v_rcp_f32_e32 v231, v231
	v_pk_mul_f32 v[142:143], v[142:143], v[218:219]
	v_pk_mul_f32 v[178:179], v[178:179], v[252:253]
	v_pk_mul_f32 v[210:211], v[210:211], v[228:229]
	v_pk_mul_f32 v[212:213], v[212:213], v[230:231]
	v_pk_fma_f32 v[218:219], v[190:191], v[118:119], v[222:223]
	v_pk_fma_f32 v[252:253], v[190:191], v[54:55], v[222:223]
	v_pk_fma_f32 v[228:229], v[190:191], v[46:47], v[222:223]
	v_pk_fma_f32 v[230:231], v[190:191], v[102:103], v[222:223]
	v_pk_fma_f32 v[218:219], v[202:203], v[54:55], v[218:219]
	v_pk_fma_f32 v[252:253], v[182:183], v[118:119], v[252:253]
	v_pk_fma_f32 v[228:229], v[182:183], v[54:55], v[228:229]
	v_pk_fma_f32 v[230:231], v[182:183], v[46:47], v[230:231]
	v_pk_fma_f32 v[252:253], v[202:203], v[46:47], v[252:253]
	v_pk_fma_f32 v[228:229], v[202:203], v[102:103], v[228:229]
	v_fmac_f32_dpp v218, v102, v182 row_shr:1 row_mask:0xf bank_mask:0xf bound_ctrl:1
	v_fmac_f32_dpp v230, v118, v202 row_shl:1 row_mask:0xf bank_mask:0xf bound_ctrl:1
	v_fmac_f32_dpp v219, v103, v183 row_shr:1 row_mask:0xf bank_mask:0xf bound_ctrl:1
	v_fmac_f32_dpp v231, v119, v203 row_shl:1 row_mask:0xf bank_mask:0xf bound_ctrl:1
	v_pk_mul_f32 v[142:143], v[142:143], v[218:219]
	v_pk_mul_f32 v[178:179], v[178:179], v[252:253]
	v_pk_mul_f32 v[210:211], v[210:211], v[228:229]
	v_pk_mul_f32 v[212:213], v[212:213], v[230:231]
	v_cvt_pk_bf16_f32 v237, v142, v143
	v_cvt_pk_bf16_f32 v241, v178, v179
	v_cvt_pk_bf16_f32 v245, v210, v211
	v_cvt_pk_bf16_f32 v249, v212, v213
	s_waitcnt lgkmcnt(4)
; __device__ __forceinline__ unsigned cvt_pk_bf16(float lo, float hi) { unsigned r; asm volatile("v_cvt_pk_bf16_f32 %0, %1, %2" : "=v"(r) : "v"(lo), "v"(hi)); return r; }
; template <int CTRL> __device__ __forceinline__ float dppz(float v) { return __int_as_float(__builtin_amdgcn_update_dpp(0, __float_as_int(v), CTRL, 0xf, 0xf, true)); }
;     __device__ __forceinline__ void operator()(f32x4 (&acc)[2][2][4][2], const Unit& u, int wr, int wc, int fr, int fq, const LAS float* rtab) const {
;     ...
;                     for (int jj = 0; jj < 4; ++jj) {
;                         const float gc = acc[ai][0][m][n][jj], uc = acc[ai][1][m][n][jj];
;                         const float gb = m > 0 ? acc[ai][0][m - 1][n][jj] : 0.f, ga = m < 3 ? acc[ai][0][m + 1][n][jj] : 0.f;
;                         const float ub = m > 0 ? acc[ai][1][m - 1][n][jj] : 0.f, ua = m < 3 ? acc[ai][1][m + 1][n][jj] : 0.f;
;                         const float gp = dppz<0x111>(gc) + dppz<0x10F>(gb), gn = dppz<0x101>(gc) + dppz<0x11F>(ga);
;                         const float up = dppz<0x111>(uc) + dppz<0x10F>(ub), un = dppz<0x101>(uc) + dppz<0x11F>(ua);
;                         const float hg = wg0[jj] * gp + wg1[jj] * gc + wg2[jj] * gn + bg[jj];
;                         const float hu = wu0[jj] * up + wu1[jj] * uc + wu2[jj] * un + bu[jj];
;                         const float sg = __builtin_amdgcn_rcpf(1.f + __builtin_amdgcn_exp2f(-1.4426950408889634f * hg));
;                         y[jj] = hg * sg * hu; }
;                     u32x2 pk; pk.x = cvt_pk_bf16(y[0], y[1]); pk.y = cvt_pk_bf16(y[2], y[3]);
;                     if (n == 0) ypk[ai][m] = pk;
;                     else {
;                         const bool deferred = (m == 0 && fr == 0) || (m == 3 && fr == 15);
;                         if (!deferred) { u32x4 w; w.x = ypk[ai][m].x; w.y = ypk[ai][m].y; w.z = pk.x; w.w = pk.y; *(u32x4*)(act + (size_t)(r64 + m * 16 + fr) * DFF + c0) = w; } }
	v_pk_fma_f32 v[142:143], v[156:157], v[120:121], v[172:173]
	v_pk_fma_f32 v[178:179], v[156:157], v[64:65], v[172:173]
	v_pk_fma_f32 v[210:211], v[156:157], v[20:21], v[172:173]
	v_pk_fma_f32 v[212:213], v[156:157], v[104:105], v[172:173]
	v_pk_fma_f32 v[142:143], v[164:165], v[64:65], v[142:143]
	v_pk_fma_f32 v[178:179], v[148:149], v[120:121], v[178:179]
	v_pk_fma_f32 v[210:211], v[148:149], v[64:65], v[210:211]
	v_pk_fma_f32 v[212:213], v[148:149], v[20:21], v[212:213]
	v_pk_fma_f32 v[178:179], v[164:165], v[20:21], v[178:179]
	v_pk_fma_f32 v[210:211], v[164:165], v[104:105], v[210:211]
	v_fmac_f32_dpp v142, v104, v148 row_shr:1 row_mask:0xf bank_mask:0xf bound_ctrl:1
	v_fmac_f32_dpp v212, v120, v164 row_shl:1 row_mask:0xf bank_mask:0xf bound_ctrl:1
	v_fmac_f32_dpp v143, v105, v149 row_shr:1 row_mask:0xf bank_mask:0xf bound_ctrl:1
	v_fmac_f32_dpp v213, v121, v165 row_shl:1 row_mask:0xf bank_mask:0xf bound_ctrl:1
	v_pk_mul_f32 v[218:219], v[142:143], s[54:55] op_sel_hi:[1,0]
	v_pk_mul_f32 v[252:253], v[178:179], s[54:55] op_sel_hi:[1,0]
	v_pk_mul_f32 v[228:229], v[210:211], s[54:55] op_sel_hi:[1,0]
	v_pk_mul_f32 v[230:231], v[212:213], s[54:55] op_sel_hi:[1,0]
	v_exp_f32_e32 v218, v218
	v_exp_f32_e32 v219, v219
	v_exp_f32_e32 v252, v252
	v_exp_f32_e32 v253, v253
	v_exp_f32_e32 v228, v228
	v_exp_f32_e32 v229, v229
	v_exp_f32_e32 v230, v230
	v_exp_f32_e32 v231, v231
	v_pk_add_f32 v[218:219], v[218:219], s[56:57] op_sel_hi:[1,0]
	v_pk_add_f32 v[252:253], v[252:253], s[56:57] op_sel_hi:[1,0]
	v_pk_add_f32 v[228:229], v[228:229], s[56:57] op_sel_hi:[1,0]
	v_pk_add_f32 v[230:231], v[230:231], s[56:57] op_sel_hi:[1,0]
	v_rcp_f32_e32 v218, v218
	v_rcp_f32_e32 v219, v219
	v_rcp_f32_e32 v252, v252
	v_rcp_f32_e32 v253, v253
	v_rcp_f32_e32 v228, v228
	v_rcp_f32_e32 v229, v229
	v_rcp_f32_e32 v230, v230
	v_rcp_f32_e32 v231, v231
	v_pk_mul_f32 v[142:143], v[142:143], v[218:219]
	v_pk_mul_f32 v[178:179], v[178:179], v[252:253]
	v_pk_mul_f32 v[210:211], v[210:211], v[228:229]
	v_pk_mul_f32 v[212:213], v[212:213], v[230:231]
	s_waitcnt lgkmcnt(0)
	v_pk_fma_f32 v[218:219], v[196:197], v[112:113], v[224:225]
	v_pk_fma_f32 v[252:253], v[196:197], v[48:49], v[224:225]
	v_pk_fma_f32 v[228:229], v[196:197], v[16:17], v[224:225]
	v_pk_fma_f32 v[230:231], v[196:197], v[96:97], v[224:225]
	v_pk_fma_f32 v[218:219], v[204:205], v[48:49], v[218:219]
	v_pk_fma_f32 v[252:253], v[184:185], v[112:113], v[252:253]
	v_pk_fma_f32 v[228:229], v[184:185], v[48:49], v[228:229]
	v_pk_fma_f32 v[230:231], v[184:185], v[16:17], v[230:231]
	v_pk_fma_f32 v[252:253], v[204:205], v[16:17], v[252:253]
	v_pk_fma_f32 v[228:229], v[204:205], v[96:97], v[228:229]
	v_fmac_f32_dpp v218, v96, v184 row_shr:1 row_mask:0xf bank_mask:0xf bound_ctrl:1
	v_fmac_f32_dpp v230, v112, v204 row_shl:1 row_mask:0xf bank_mask:0xf bound_ctrl:1
	v_fmac_f32_dpp v219, v97, v185 row_shr:1 row_mask:0xf bank_mask:0xf bound_ctrl:1
	v_fmac_f32_dpp v231, v113, v205 row_shl:1 row_mask:0xf bank_mask:0xf bound_ctrl:1
	v_pk_mul_f32 v[142:143], v[142:143], v[218:219]
	v_pk_mul_f32 v[178:179], v[178:179], v[252:253]
	v_pk_mul_f32 v[210:211], v[210:211], v[228:229]
	v_pk_mul_f32 v[212:213], v[212:213], v[230:231]
	v_cvt_pk_bf16_f32 v238, v142, v143
	v_cvt_pk_bf16_f32 v242, v178, v179
	v_cvt_pk_bf16_f32 v246, v210, v211
	v_cvt_pk_bf16_f32 v250, v212, v213
	v_pk_fma_f32 v[142:143], v[158:159], v[122:123], v[174:175]
	v_pk_fma_f32 v[178:179], v[158:159], v[66:67], v[174:175]
	v_pk_fma_f32 v[210:211], v[158:159], v[22:23], v[174:175]
	v_pk_fma_f32 v[212:213], v[158:159], v[106:107], v[174:175]
	v_pk_fma_f32 v[142:143], v[166:167], v[66:67], v[142:143]
	v_pk_fma_f32 v[178:179], v[150:151], v[122:123], v[178:179]
	v_pk_fma_f32 v[210:211], v[150:151], v[66:67], v[210:211]
	v_pk_fma_f32 v[212:213], v[150:151], v[22:23], v[212:213]
	v_pk_fma_f32 v[178:179], v[166:167], v[22:23], v[178:179]
	v_pk_fma_f32 v[210:211], v[166:167], v[106:107], v[210:211]
	v_fmac_f32_dpp v142, v106, v150 row_shr:1 row_mask:0xf bank_mask:0xf bound_ctrl:1
	v_fmac_f32_dpp v212, v122, v166 row_shl:1 row_mask:0xf bank_mask:0xf bound_ctrl:1
	v_fmac_f32_dpp v143, v107, v151 row_shr:1 row_mask:0xf bank_mask:0xf bound_ctrl:1
	v_fmac_f32_dpp v213, v123, v167 row_shl:1 row_mask:0xf bank_mask:0xf bound_ctrl:1
	v_pk_mul_f32 v[218:219], v[142:143], s[54:55] op_sel_hi:[1,0]
	v_pk_mul_f32 v[252:253], v[178:179], s[54:55] op_sel_hi:[1,0]
	v_pk_mul_f32 v[228:229], v[210:211], s[54:55] op_sel_hi:[1,0]
	v_pk_mul_f32 v[230:231], v[212:213], s[54:55] op_sel_hi:[1,0]
	v_exp_f32_e32 v218, v218
	v_exp_f32_e32 v219, v219
	v_exp_f32_e32 v252, v252
	v_exp_f32_e32 v253, v253
	v_exp_f32_e32 v228, v228
	v_exp_f32_e32 v229, v229
	v_exp_f32_e32 v230, v230
	v_exp_f32_e32 v231, v231
	v_pk_add_f32 v[218:219], v[218:219], s[56:57] op_sel_hi:[1,0]
	v_pk_add_f32 v[252:253], v[252:253], s[56:57] op_sel_hi:[1,0]
	v_pk_add_f32 v[228:229], v[228:229], s[56:57] op_sel_hi:[1,0]
	v_pk_add_f32 v[230:231], v[230:231], s[56:57] op_sel_hi:[1,0]
	v_rcp_f32_e32 v218, v218
	v_rcp_f32_e32 v219, v219
	v_rcp_f32_e32 v252, v252
	v_rcp_f32_e32 v253, v253
	v_rcp_f32_e32 v228, v228
	v_rcp_f32_e32 v229, v229
	v_rcp_f32_e32 v230, v230
	v_rcp_f32_e32 v231, v231
	v_pk_mul_f32 v[142:143], v[142:143], v[218:219]
	v_pk_mul_f32 v[178:179], v[178:179], v[252:253]
	v_pk_mul_f32 v[210:211], v[210:211], v[228:229]
	v_pk_mul_f32 v[212:213], v[212:213], v[230:231]
	v_pk_fma_f32 v[218:219], v[198:199], v[114:115], v[226:227]
	v_pk_fma_f32 v[252:253], v[198:199], v[50:51], v[226:227]
	v_pk_fma_f32 v[228:229], v[198:199], v[18:19], v[226:227]
	v_pk_fma_f32 v[230:231], v[198:199], v[98:99], v[226:227]
; __device__ __forceinline__ unsigned cvt_pk_bf16(float lo, float hi) { unsigned r; asm volatile("v_cvt_pk_bf16_f32 %0, %1, %2" : "=v"(r) : "v"(lo), "v"(hi)); return r; }
; template <int CTRL> __device__ __forceinline__ float dppz(float v) { return __int_as_float(__builtin_amdgcn_update_dpp(0, __float_as_int(v), CTRL, 0xf, 0xf, true)); }
;     __device__ __forceinline__ void operator()(f32x4 (&acc)[2][2][4][2], const Unit& u, int wr, int wc, int fr, int fq, const LAS float* rtab) const {
;     ...
;                     for (int jj = 0; jj < 4; ++jj) {
;                         const float gc = acc[ai][0][m][n][jj], uc = acc[ai][1][m][n][jj];
;                         const float gb = m > 0 ? acc[ai][0][m - 1][n][jj] : 0.f, ga = m < 3 ? acc[ai][0][m + 1][n][jj] : 0.f;
;                         const float ub = m > 0 ? acc[ai][1][m - 1][n][jj] : 0.f, ua = m < 3 ? acc[ai][1][m + 1][n][jj] : 0.f;
;                         const float gp = dppz<0x111>(gc) + dppz<0x10F>(gb), gn = dppz<0x101>(gc) + dppz<0x11F>(ga);
;                         const float up = dppz<0x111>(uc) + dppz<0x10F>(ub), un = dppz<0x101>(uc) + dppz<0x11F>(ua);
;                         const float hg = wg0[jj] * gp + wg1[jj] * gc + wg2[jj] * gn + bg[jj];
;                         const float hu = wu0[jj] * up + wu1[jj] * uc + wu2[jj] * un + bu[jj];
;                         const float sg = __builtin_amdgcn_rcpf(1.f + __builtin_amdgcn_exp2f(-1.4426950408889634f * hg));
;                         y[jj] = hg * sg * hu; }
;                     u32x2 pk; pk.x = cvt_pk_bf16(y[0], y[1]); pk.y = cvt_pk_bf16(y[2], y[3]);
;                     if (n == 0) ypk[ai][m] = pk;
;                     else {
;                         const bool deferred = (m == 0 && fr == 0) || (m == 3 && fr == 15);
;                         if (!deferred) { u32x4 w; w.x = ypk[ai][m].x; w.y = ypk[ai][m].y; w.z = pk.x; w.w = pk.y; *(u32x4*)(act + (size_t)(r64 + m * 16 + fr) * DFF + c0) = w; } }
	v_pk_fma_f32 v[218:219], v[206:207], v[50:51], v[218:219]
	v_pk_fma_f32 v[252:253], v[186:187], v[114:115], v[252:253]
	v_pk_fma_f32 v[228:229], v[186:187], v[50:51], v[228:229]
	v_pk_fma_f32 v[230:231], v[186:187], v[18:19], v[230:231]
	v_pk_fma_f32 v[252:253], v[206:207], v[18:19], v[252:253]
	v_pk_fma_f32 v[228:229], v[206:207], v[98:99], v[228:229]
	v_fmac_f32_dpp v218, v98, v186 row_shr:1 row_mask:0xf bank_mask:0xf bound_ctrl:1
	v_fmac_f32_dpp v230, v114, v206 row_shl:1 row_mask:0xf bank_mask:0xf bound_ctrl:1
	v_fmac_f32_dpp v219, v99, v187 row_shr:1 row_mask:0xf bank_mask:0xf bound_ctrl:1
	v_fmac_f32_dpp v231, v115, v207 row_shl:1 row_mask:0xf bank_mask:0xf bound_ctrl:1
	v_pk_mul_f32 v[142:143], v[142:143], v[218:219]
	v_pk_mul_f32 v[178:179], v[178:179], v[252:253]
	v_pk_mul_f32 v[210:211], v[210:211], v[228:229]
	v_pk_mul_f32 v[212:213], v[212:213], v[230:231]
	v_cvt_pk_bf16_f32 v239, v142, v143
	v_cvt_pk_bf16_f32 v243, v178, v179
	v_cvt_pk_bf16_f32 v247, v210, v211
	v_cvt_pk_bf16_f32 v251, v212, v213
	s_mov_b64 s[58:59], s[28:29]
	s_mov_b64 exec, s[12:13]
	global_store_dwordx4 v234, v[236:239], s[58:59]
	s_mov_b64 exec, -1
	s_add_u32 s58, s28, 0x2c00
	s_addc_u32 s59, s29, 0
	global_store_dwordx4 v234, v[240:243], s[58:59]
	s_add_u32 s58, s28, 0x5800
	s_addc_u32 s59, s29, 0
	global_store_dwordx4 v234, v[244:247], s[58:59]
	s_add_u32 s58, s28, 0x8400
	s_addc_u32 s59, s29, 0
	s_mov_b64 exec, s[10:11]
	global_store_dwordx4 v234, v[248:251], s[58:59]
	s_mov_b64 exec, -1
	v_pk_fma_f32 v[142:143], v[152:153], v[92:93], v[168:169]
	v_pk_fma_f32 v[178:179], v[152:153], v[36:37], v[168:169]
	v_pk_fma_f32 v[210:211], v[152:153], v[32:33], v[168:169]
	v_pk_fma_f32 v[212:213], v[152:153], v[76:77], v[168:169]
	v_pk_fma_f32 v[142:143], v[160:161], v[36:37], v[142:143]
	v_pk_fma_f32 v[178:179], v[144:145], v[92:93], v[178:179]
	v_pk_fma_f32 v[210:211], v[144:145], v[36:37], v[210:211]
	v_pk_fma_f32 v[212:213], v[144:145], v[32:33], v[212:213]
	v_pk_fma_f32 v[178:179], v[160:161], v[32:33], v[178:179]
	v_pk_fma_f32 v[210:211], v[160:161], v[76:77], v[210:211]
	v_fmac_f32_dpp v142, v76, v144 row_shr:1 row_mask:0xf bank_mask:0xf bound_ctrl:1
	v_fmac_f32_dpp v212, v92, v160 row_shl:1 row_mask:0xf bank_mask:0xf bound_ctrl:1
	v_fmac_f32_dpp v143, v77, v145 row_shr:1 row_mask:0xf bank_mask:0xf bound_ctrl:1
	v_fmac_f32_dpp v213, v93, v161 row_shl:1 row_mask:0xf bank_mask:0xf bound_ctrl:1
	v_pk_mul_f32 v[218:219], v[142:143], s[54:55] op_sel_hi:[1,0]
	v_pk_mul_f32 v[252:253], v[178:179], s[54:55] op_sel_hi:[1,0]
	v_pk_mul_f32 v[228:229], v[210:211], s[54:55] op_sel_hi:[1,0]
	v_pk_mul_f32 v[230:231], v[212:213], s[54:55] op_sel_hi:[1,0]
	v_exp_f32_e32 v218, v218
	v_exp_f32_e32 v219, v219
	v_exp_f32_e32 v252, v252
	v_exp_f32_e32 v253, v253
	v_exp_f32_e32 v228, v228
	v_exp_f32_e32 v229, v229
	v_exp_f32_e32 v230, v230
	v_exp_f32_e32 v231, v231
	v_pk_add_f32 v[218:219], v[218:219], s[56:57] op_sel_hi:[1,0]
	v_pk_add_f32 v[252:253], v[252:253], s[56:57] op_sel_hi:[1,0]
	v_pk_add_f32 v[228:229], v[228:229], s[56:57] op_sel_hi:[1,0]
	v_pk_add_f32 v[230:231], v[230:231], s[56:57] op_sel_hi:[1,0]
	v_rcp_f32_e32 v218, v218
	v_rcp_f32_e32 v219, v219
	v_rcp_f32_e32 v252, v252
	v_rcp_f32_e32 v253, v253
	v_rcp_f32_e32 v228, v228
	v_rcp_f32_e32 v229, v229
	v_rcp_f32_e32 v230, v230
	v_rcp_f32_e32 v231, v231
	v_pk_mul_f32 v[142:143], v[142:143], v[218:219]
	v_pk_mul_f32 v[178:179], v[178:179], v[252:253]
	v_pk_mul_f32 v[210:211], v[210:211], v[228:229]
	v_pk_mul_f32 v[212:213], v[212:213], v[230:231]
	v_pk_fma_f32 v[218:219], v[188:189], v[84:85], v[220:221]
	v_pk_fma_f32 v[252:253], v[188:189], v[28:29], v[220:221]
	v_pk_fma_f32 v[228:229], v[188:189], v[24:25], v[220:221]
	v_pk_fma_f32 v[230:231], v[188:189], v[72:73], v[220:221]
	v_pk_fma_f32 v[218:219], v[200:201], v[28:29], v[218:219]
	v_pk_fma_f32 v[252:253], v[180:181], v[84:85], v[252:253]
	v_pk_fma_f32 v[228:229], v[180:181], v[28:29], v[228:229]
	v_pk_fma_f32 v[230:231], v[180:181], v[24:25], v[230:231]
	v_pk_fma_f32 v[252:253], v[200:201], v[24:25], v[252:253]
	v_pk_fma_f32 v[228:229], v[200:201], v[72:73], v[228:229]
	v_fmac_f32_dpp v218, v72, v180 row_shr:1 row_mask:0xf bank_mask:0xf bound_ctrl:1
	v_fmac_f32_dpp v230, v84, v200 row_shl:1 row_mask:0xf bank_mask:0xf bound_ctrl:1
	v_fmac_f32_dpp v219, v73, v181 row_shr:1 row_mask:0xf bank_mask:0xf bound_ctrl:1
	v_fmac_f32_dpp v231, v85, v201 row_shl:1 row_mask:0xf bank_mask:0xf bound_ctrl:1
	v_pk_mul_f32 v[142:143], v[142:143], v[218:219]
	v_pk_mul_f32 v[178:179], v[178:179], v[252:253]
	v_pk_mul_f32 v[210:211], v[210:211], v[228:229]
	v_pk_mul_f32 v[212:213], v[212:213], v[230:231]
	v_cvt_pk_bf16_f32 v236, v142, v143
	v_cvt_pk_bf16_f32 v240, v178, v179
	v_cvt_pk_bf16_f32 v244, v210, v211
	v_cvt_pk_bf16_f32 v248, v212, v213
	v_pk_fma_f32 v[142:143], v[154:155], v[94:95], v[170:171]
	v_pk_fma_f32 v[178:179], v[154:155], v[38:39], v[170:171]
	v_pk_fma_f32 v[210:211], v[154:155], v[34:35], v[170:171]
	v_pk_fma_f32 v[212:213], v[154:155], v[78:79], v[170:171]
	v_pk_fma_f32 v[142:143], v[162:163], v[38:39], v[142:143]
	v_pk_fma_f32 v[178:179], v[146:147], v[94:95], v[178:179]
	v_pk_fma_f32 v[210:211], v[146:147], v[38:39], v[210:211]
	v_pk_fma_f32 v[212:213], v[146:147], v[34:35], v[212:213]
	v_pk_fma_f32 v[178:179], v[162:163], v[34:35], v[178:179]
	v_pk_fma_f32 v[210:211], v[162:163], v[78:79], v[210:211]
	v_fmac_f32_dpp v142, v78, v146 row_shr:1 row_mask:0xf bank_mask:0xf bound_ctrl:1
	v_fmac_f32_dpp v212, v94, v162 row_shl:1 row_mask:0xf bank_mask:0xf bound_ctrl:1
	v_fmac_f32_dpp v143, v79, v147 row_shr:1 row_mask:0xf bank_mask:0xf bound_ctrl:1
; __device__ __forceinline__ unsigned cvt_pk_bf16(float lo, float hi) { unsigned r; asm volatile("v_cvt_pk_bf16_f32 %0, %1, %2" : "=v"(r) : "v"(lo), "v"(hi)); return r; }
; template <int CTRL> __device__ __forceinline__ float dppz(float v) { return __int_as_float(__builtin_amdgcn_update_dpp(0, __float_as_int(v), CTRL, 0xf, 0xf, true)); }
;     __device__ __forceinline__ void operator()(f32x4 (&acc)[2][2][4][2], const Unit& u, int wr, int wc, int fr, int fq, const LAS float* rtab) const {
;     ...
;                     for (int jj = 0; jj < 4; ++jj) {
;                         const float gc = acc[ai][0][m][n][jj], uc = acc[ai][1][m][n][jj];
;                         const float gb = m > 0 ? acc[ai][0][m - 1][n][jj] : 0.f, ga = m < 3 ? acc[ai][0][m + 1][n][jj] : 0.f;
;                         const float ub = m > 0 ? acc[ai][1][m - 1][n][jj] : 0.f, ua = m < 3 ? acc[ai][1][m + 1][n][jj] : 0.f;
;                         const float gp = dppz<0x111>(gc) + dppz<0x10F>(gb), gn = dppz<0x101>(gc) + dppz<0x11F>(ga);
;                         const float up = dppz<0x111>(uc) + dppz<0x10F>(ub), un = dppz<0x101>(uc) + dppz<0x11F>(ua);
;                         const float hg = wg0[jj] * gp + wg1[jj] * gc + wg2[jj] * gn + bg[jj];
;                         const float hu = wu0[jj] * up + wu1[jj] * uc + wu2[jj] * un + bu[jj];
;                         const float sg = __builtin_amdgcn_rcpf(1.f + __builtin_amdgcn_exp2f(-1.4426950408889634f * hg));
;                         y[jj] = hg * sg * hu; }
;                     u32x2 pk; pk.x = cvt_pk_bf16(y[0], y[1]); pk.y = cvt_pk_bf16(y[2], y[3]);
;                     if (n == 0) ypk[ai][m] = pk;
;                     else {
;                         const bool deferred = (m == 0 && fr == 0) || (m == 3 && fr == 15);
;                         if (!deferred) { u32x4 w; w.x = ypk[ai][m].x; w.y = ypk[ai][m].y; w.z = pk.x; w.w = pk.y; *(u32x4*)(act + (size_t)(r64 + m * 16 + fr) * DFF + c0) = w; } }
	v_fmac_f32_dpp v213, v95, v163 row_shl:1 row_mask:0xf bank_mask:0xf bound_ctrl:1
	v_pk_mul_f32 v[218:219], v[142:143], s[54:55] op_sel_hi:[1,0]
	v_pk_mul_f32 v[252:253], v[178:179], s[54:55] op_sel_hi:[1,0]
	v_pk_mul_f32 v[228:229], v[210:211], s[54:55] op_sel_hi:[1,0]
	v_pk_mul_f32 v[230:231], v[212:213], s[54:55] op_sel_hi:[1,0]
	v_exp_f32_e32 v218, v218
	v_exp_f32_e32 v219, v219
	v_exp_f32_e32 v252, v252
	v_exp_f32_e32 v253, v253
	v_exp_f32_e32 v228, v228
	v_exp_f32_e32 v229, v229
	v_exp_f32_e32 v230, v230
	v_exp_f32_e32 v231, v231
	v_pk_add_f32 v[218:219], v[218:219], s[56:57] op_sel_hi:[1,0]
	v_pk_add_f32 v[252:253], v[252:253], s[56:57] op_sel_hi:[1,0]
	v_pk_add_f32 v[228:229], v[228:229], s[56:57] op_sel_hi:[1,0]
	v_pk_add_f32 v[230:231], v[230:231], s[56:57] op_sel_hi:[1,0]
	v_rcp_f32_e32 v218, v218
	v_rcp_f32_e32 v219, v219
	v_rcp_f32_e32 v252, v252
	v_rcp_f32_e32 v253, v253
	v_rcp_f32_e32 v228, v228
	v_rcp_f32_e32 v229, v229
	v_rcp_f32_e32 v230, v230
	v_rcp_f32_e32 v231, v231
	v_pk_mul_f32 v[142:143], v[142:143], v[218:219]
	v_pk_mul_f32 v[178:179], v[178:179], v[252:253]
	v_pk_mul_f32 v[210:211], v[210:211], v[228:229]
	v_pk_mul_f32 v[212:213], v[212:213], v[230:231]
	v_pk_fma_f32 v[218:219], v[190:191], v[86:87], v[222:223]
	v_pk_fma_f32 v[252:253], v[190:191], v[30:31], v[222:223]
	v_pk_fma_f32 v[228:229], v[190:191], v[26:27], v[222:223]
	v_pk_fma_f32 v[230:231], v[190:191], v[74:75], v[222:223]
	v_pk_fma_f32 v[218:219], v[202:203], v[30:31], v[218:219]
	v_pk_fma_f32 v[252:253], v[182:183], v[86:87], v[252:253]
	v_pk_fma_f32 v[228:229], v[182:183], v[30:31], v[228:229]
	v_pk_fma_f32 v[230:231], v[182:183], v[26:27], v[230:231]
	v_pk_fma_f32 v[252:253], v[202:203], v[26:27], v[252:253]
	v_pk_fma_f32 v[228:229], v[202:203], v[74:75], v[228:229]
	v_fmac_f32_dpp v218, v74, v182 row_shr:1 row_mask:0xf bank_mask:0xf bound_ctrl:1
	v_fmac_f32_dpp v230, v86, v202 row_shl:1 row_mask:0xf bank_mask:0xf bound_ctrl:1
	v_fmac_f32_dpp v219, v75, v183 row_shr:1 row_mask:0xf bank_mask:0xf bound_ctrl:1
	v_fmac_f32_dpp v231, v87, v203 row_shl:1 row_mask:0xf bank_mask:0xf bound_ctrl:1
	v_pk_mul_f32 v[142:143], v[142:143], v[218:219]
	v_pk_mul_f32 v[178:179], v[178:179], v[252:253]
	v_pk_mul_f32 v[210:211], v[210:211], v[228:229]
	v_pk_mul_f32 v[212:213], v[212:213], v[230:231]
	v_cvt_pk_bf16_f32 v237, v142, v143
	v_cvt_pk_bf16_f32 v241, v178, v179
	v_cvt_pk_bf16_f32 v245, v210, v211
	v_cvt_pk_bf16_f32 v249, v212, v213
	v_pk_fma_f32 v[142:143], v[156:157], v[88:89], v[172:173]
	v_pk_fma_f32 v[178:179], v[156:157], v[12:13], v[172:173]
	v_pk_fma_f32 v[210:211], v[156:157], v[4:5], v[172:173]
	v_pk_fma_f32 v[212:213], v[156:157], v[56:57], v[172:173]
	v_pk_fma_f32 v[142:143], v[164:165], v[12:13], v[142:143]
	v_pk_fma_f32 v[178:179], v[148:149], v[88:89], v[178:179]
	v_pk_fma_f32 v[210:211], v[148:149], v[12:13], v[210:211]
	v_pk_fma_f32 v[212:213], v[148:149], v[4:5], v[212:213]
	v_pk_fma_f32 v[178:179], v[164:165], v[4:5], v[178:179]
	v_pk_fma_f32 v[210:211], v[164:165], v[56:57], v[210:211]
	v_fmac_f32_dpp v142, v56, v148 row_shr:1 row_mask:0xf bank_mask:0xf bound_ctrl:1
	v_fmac_f32_dpp v212, v88, v164 row_shl:1 row_mask:0xf bank_mask:0xf bound_ctrl:1
	v_fmac_f32_dpp v143, v57, v149 row_shr:1 row_mask:0xf bank_mask:0xf bound_ctrl:1
	v_fmac_f32_dpp v213, v89, v165 row_shl:1 row_mask:0xf bank_mask:0xf bound_ctrl:1
	v_pk_mul_f32 v[218:219], v[142:143], s[54:55] op_sel_hi:[1,0]
	v_pk_mul_f32 v[252:253], v[178:179], s[54:55] op_sel_hi:[1,0]
	v_pk_mul_f32 v[228:229], v[210:211], s[54:55] op_sel_hi:[1,0]
	v_pk_mul_f32 v[230:231], v[212:213], s[54:55] op_sel_hi:[1,0]
	v_exp_f32_e32 v218, v218
	v_exp_f32_e32 v219, v219
	v_exp_f32_e32 v252, v252
	v_exp_f32_e32 v253, v253
	v_exp_f32_e32 v228, v228
	v_exp_f32_e32 v229, v229
	v_exp_f32_e32 v230, v230
	v_exp_f32_e32 v231, v231
	v_pk_add_f32 v[218:219], v[218:219], s[56:57] op_sel_hi:[1,0]
	v_pk_add_f32 v[252:253], v[252:253], s[56:57] op_sel_hi:[1,0]
	v_pk_add_f32 v[228:229], v[228:229], s[56:57] op_sel_hi:[1,0]
	v_pk_add_f32 v[230:231], v[230:231], s[56:57] op_sel_hi:[1,0]
	v_rcp_f32_e32 v218, v218
	v_rcp_f32_e32 v219, v219
	v_rcp_f32_e32 v252, v252
	v_rcp_f32_e32 v253, v253
	v_rcp_f32_e32 v228, v228
	v_rcp_f32_e32 v229, v229
	v_rcp_f32_e32 v230, v230
	v_rcp_f32_e32 v231, v231
	v_pk_mul_f32 v[142:143], v[142:143], v[218:219]
	v_pk_mul_f32 v[178:179], v[178:179], v[252:253]
	v_pk_mul_f32 v[210:211], v[210:211], v[228:229]
	v_pk_mul_f32 v[212:213], v[212:213], v[230:231]
	v_pk_fma_f32 v[218:219], v[196:197], v[80:81], v[224:225]
	v_pk_fma_f32 v[252:253], v[196:197], v[8:9], v[224:225]
	v_pk_fma_f32 v[228:229], v[196:197], v[0:1], v[224:225]
	v_pk_fma_f32 v[230:231], v[196:197], v[40:41], v[224:225]
	v_pk_fma_f32 v[218:219], v[204:205], v[8:9], v[218:219]
; __device__ __forceinline__ unsigned cvt_pk_bf16(float lo, float hi) { unsigned r; asm volatile("v_cvt_pk_bf16_f32 %0, %1, %2" : "=v"(r) : "v"(lo), "v"(hi)); return r; }
;     __device__ __forceinline__ void operator()(f32x4 (&acc)[2][2][4][2], const Unit& u, int wr, int wc, int fr, int fq, const LAS float* rtab) const {
;     ...
;                     for (int jj = 0; jj < 4; ++jj) {
;                         const float gc = acc[ai][0][m][n][jj], uc = acc[ai][1][m][n][jj];
;                         const float gb = m > 0 ? acc[ai][0][m - 1][n][jj] : 0.f, ga = m < 3 ? acc[ai][0][m + 1][n][jj] : 0.f;
;                         const float ub = m > 0 ? acc[ai][1][m - 1][n][jj] : 0.f, ua = m < 3 ? acc[ai][1][m + 1][n][jj] : 0.f;
;                         const float gp = dppz<0x111>(gc) + dppz<0x10F>(gb), gn = dppz<0x101>(gc) + dppz<0x11F>(ga);
;                         const float up = dppz<0x111>(uc) + dppz<0x10F>(ub), un = dppz<0x101>(uc) + dppz<0x11F>(ua);
;                         const float hg = wg0[jj] * gp + wg1[jj] * gc + wg2[jj] * gn + bg[jj];
;                         const float hu = wu0[jj] * up + wu1[jj] * uc + wu2[jj] * un + bu[jj];
;                         const float sg = __builtin_amdgcn_rcpf(1.f + __builtin_amdgcn_exp2f(-1.4426950408889634f * hg));
;                         y[jj] = hg * sg * hu; }
;                     u32x2 pk; pk.x = cvt_pk_bf16(y[0], y[1]); pk.y = cvt_pk_bf16(y[2], y[3]);
;                     if (n == 0) ypk[ai][m] = pk;
;                     else {
;                         const bool deferred = (m == 0 && fr == 0) || (m == 3 && fr == 15);
;                         if (!deferred) { u32x4 w; w.x = ypk[ai][m].x; w.y = ypk[ai][m].y; w.z = pk.x; w.w = pk.y; *(u32x4*)(act + (size_t)(r64 + m * 16 + fr) * DFF + c0) = w; } }
; template <class Epi, bool KREV = false>
; __device__ __forceinline__ void gemm_phase(LAS unsigned char* lds, const Gemm g, const StaticOrder& S, const Epi& E, int wave_s) {
;     ...
;         if (!has_next) break;
; #pragma unroll
;         for (int a = 0; a < 2; ++a)
; #pragma unroll
;             for (int b = 0; b < 2; ++b)
; #pragma unroll
;                 for (int m = 0; m < 4; ++m)
; #pragma unroll
;                     for (int n = 0; n < 2; ++n) acc[a][b][m][n] = (f32x4){0.f, 0.f, 0.f, 0.f};
;         cur = nxt; cA = nA; cB = nB; ++ui;
;         if (wr == 1) PG8_BAR;
;     }
	v_pk_fma_f32 v[252:253], v[184:185], v[80:81], v[252:253]
	v_pk_fma_f32 v[228:229], v[184:185], v[8:9], v[228:229]
	v_pk_fma_f32 v[230:231], v[184:185], v[0:1], v[230:231]
	v_pk_fma_f32 v[252:253], v[204:205], v[0:1], v[252:253]
	v_pk_fma_f32 v[228:229], v[204:205], v[40:41], v[228:229]
	v_fmac_f32_dpp v218, v40, v184 row_shr:1 row_mask:0xf bank_mask:0xf bound_ctrl:1
	v_fmac_f32_dpp v230, v80, v204 row_shl:1 row_mask:0xf bank_mask:0xf bound_ctrl:1
	v_fmac_f32_dpp v219, v41, v185 row_shr:1 row_mask:0xf bank_mask:0xf bound_ctrl:1
	v_fmac_f32_dpp v231, v81, v205 row_shl:1 row_mask:0xf bank_mask:0xf bound_ctrl:1
	v_pk_mul_f32 v[142:143], v[142:143], v[218:219]
	v_pk_mul_f32 v[178:179], v[178:179], v[252:253]
	v_pk_mul_f32 v[210:211], v[210:211], v[228:229]
	v_pk_mul_f32 v[212:213], v[212:213], v[230:231]
	v_cvt_pk_bf16_f32 v238, v142, v143
	v_cvt_pk_bf16_f32 v242, v178, v179
	v_cvt_pk_bf16_f32 v246, v210, v211
	v_cvt_pk_bf16_f32 v250, v212, v213
	v_pk_fma_f32 v[142:143], v[158:159], v[90:91], v[174:175]
	v_pk_fma_f32 v[178:179], v[158:159], v[14:15], v[174:175]
	v_pk_fma_f32 v[210:211], v[158:159], v[6:7], v[174:175]
	v_pk_fma_f32 v[212:213], v[158:159], v[58:59], v[174:175]
	v_pk_fma_f32 v[142:143], v[166:167], v[14:15], v[142:143]
	v_pk_fma_f32 v[178:179], v[150:151], v[90:91], v[178:179]
	v_pk_fma_f32 v[210:211], v[150:151], v[14:15], v[210:211]
	v_pk_fma_f32 v[212:213], v[150:151], v[6:7], v[212:213]
	v_pk_fma_f32 v[178:179], v[166:167], v[6:7], v[178:179]
	v_pk_fma_f32 v[210:211], v[166:167], v[58:59], v[210:211]
	v_fmac_f32_dpp v142, v58, v150 row_shr:1 row_mask:0xf bank_mask:0xf bound_ctrl:1
	v_fmac_f32_dpp v212, v90, v166 row_shl:1 row_mask:0xf bank_mask:0xf bound_ctrl:1
	v_fmac_f32_dpp v143, v59, v151 row_shr:1 row_mask:0xf bank_mask:0xf bound_ctrl:1
	v_fmac_f32_dpp v213, v91, v167 row_shl:1 row_mask:0xf bank_mask:0xf bound_ctrl:1
	v_pk_mul_f32 v[218:219], v[142:143], s[54:55] op_sel_hi:[1,0]
	v_pk_mul_f32 v[252:253], v[178:179], s[54:55] op_sel_hi:[1,0]
	v_pk_mul_f32 v[228:229], v[210:211], s[54:55] op_sel_hi:[1,0]
	v_pk_mul_f32 v[230:231], v[212:213], s[54:55] op_sel_hi:[1,0]
	v_exp_f32_e32 v218, v218
	v_exp_f32_e32 v219, v219
	v_exp_f32_e32 v252, v252
	v_exp_f32_e32 v253, v253
	v_exp_f32_e32 v228, v228
	v_exp_f32_e32 v229, v229
	v_exp_f32_e32 v230, v230
	v_exp_f32_e32 v231, v231
	v_pk_add_f32 v[218:219], v[218:219], s[56:57] op_sel_hi:[1,0]
	v_pk_add_f32 v[252:253], v[252:253], s[56:57] op_sel_hi:[1,0]
	v_pk_add_f32 v[228:229], v[228:229], s[56:57] op_sel_hi:[1,0]
	v_pk_add_f32 v[230:231], v[230:231], s[56:57] op_sel_hi:[1,0]
	v_rcp_f32_e32 v218, v218
	v_rcp_f32_e32 v219, v219
	v_rcp_f32_e32 v252, v252
	v_rcp_f32_e32 v253, v253
	v_rcp_f32_e32 v228, v228
	v_rcp_f32_e32 v229, v229
	v_rcp_f32_e32 v230, v230
	v_rcp_f32_e32 v231, v231
	v_pk_mul_f32 v[142:143], v[142:143], v[218:219]
	v_pk_mul_f32 v[178:179], v[178:179], v[252:253]
	v_pk_mul_f32 v[210:211], v[210:211], v[228:229]
	v_pk_mul_f32 v[212:213], v[212:213], v[230:231]
	v_pk_fma_f32 v[218:219], v[198:199], v[82:83], v[226:227]
	v_pk_fma_f32 v[252:253], v[198:199], v[10:11], v[226:227]
	v_pk_fma_f32 v[228:229], v[198:199], v[2:3], v[226:227]
	v_pk_fma_f32 v[230:231], v[198:199], v[42:43], v[226:227]
	v_pk_fma_f32 v[218:219], v[206:207], v[10:11], v[218:219]
	v_pk_fma_f32 v[252:253], v[186:187], v[82:83], v[252:253]
	v_pk_fma_f32 v[228:229], v[186:187], v[10:11], v[228:229]
	v_pk_fma_f32 v[230:231], v[186:187], v[2:3], v[230:231]
	v_pk_fma_f32 v[252:253], v[206:207], v[2:3], v[252:253]
	v_pk_fma_f32 v[228:229], v[206:207], v[42:43], v[228:229]
	v_fmac_f32_dpp v218, v42, v186 row_shr:1 row_mask:0xf bank_mask:0xf bound_ctrl:1
	v_fmac_f32_dpp v230, v82, v206 row_shl:1 row_mask:0xf bank_mask:0xf bound_ctrl:1
	v_fmac_f32_dpp v219, v43, v187 row_shr:1 row_mask:0xf bank_mask:0xf bound_ctrl:1
	v_fmac_f32_dpp v231, v83, v207 row_shl:1 row_mask:0xf bank_mask:0xf bound_ctrl:1
	v_pk_mul_f32 v[142:143], v[142:143], v[218:219]
	v_pk_mul_f32 v[178:179], v[178:179], v[252:253]
	v_pk_mul_f32 v[210:211], v[210:211], v[228:229]
	v_pk_mul_f32 v[212:213], v[212:213], v[230:231]
	v_cvt_pk_bf16_f32 v239, v142, v143
	v_cvt_pk_bf16_f32 v243, v178, v179
	v_cvt_pk_bf16_f32 v247, v210, v211
	v_cvt_pk_bf16_f32 v251, v212, v213
	s_add_u32 s58, s28, 0x160000
	s_addc_u32 s59, s29, 0
	s_mov_b64 exec, s[12:13]
	global_store_dwordx4 v234, v[236:239], s[58:59]
	s_mov_b64 exec, -1
	s_add_u32 s58, s28, 0x162c00
	s_addc_u32 s59, s29, 0
	global_store_dwordx4 v234, v[240:243], s[58:59]
	s_add_u32 s58, s28, 0x165800
	s_addc_u32 s59, s29, 0
	global_store_dwordx4 v234, v[244:247], s[58:59]
	s_add_u32 s58, s28, 0x168400
	s_addc_u32 s59, s29, 0
	s_mov_b64 exec, s[10:11]
	global_store_dwordx4 v234, v[248:251], s[58:59]
	s_mov_b64 exec, -1
	s_andn2_b64 vcc, exec, s[52:53]
	s_mov_b64 s[52:53], -1
	s_cbranch_vccnz .LBB0_834
